# work-queue next-item atomic issued at the start of the item epilogue (P2b diff/SB, P2a FoX), no vmcnt drain at the fetch
# speedup vs baseline: 1.0014x; 1.0014x over previous
; __global__ void __launch_bounds__(512) hymba_fwd(Args a) {
;     ...
;         if (IN(pb + 1)) {
;             WSPTRS
;             ScanP sp{proj, mixed, misc, a.rwkv_mu + l * 1600, a.rwkv_w_up + l * 32 * 512, a.rwkv_w0 + l * 512, a.rwkv_a_up + l * 32 * 512, a.rwkv_a0 + l * 512,
;                      a.rwkv_kkr + l * 3 * 512, a.rwkv_ln_gain + l * 512, a.rwkv_ln_bias + l * 512, a.out_gain + l * 2048,
;                      (bf16_t*)(ws_ + WS_Q), (float*)(ws_ + WS_BON), (float*)(ws_ + WS_HE), (float*)(ws_ + WS_PE)};
;             AttnP ap{proj, mixed, misc, a.qk_gain + l * 256, a.out_gain + l * 2048, biasT, a.forget_bias + l * 8, 0.f, 0.f};
;             for (;;) {
;                 const int idx = next_item(ctl + pb + 1, qslot);
;                 if (idx >= 256 + 1024) break;
.LBB0_207:
	s_andn2_b64 vcc, exec, s[0:1]
	s_cbranch_vccnz .LBB0_362
	s_mov_b64 s[24:25], s[68:69]
	s_add_u32 s68, s24, 0x6a00000
	s_addc_u32 s69, s25, 0
	s_mov_b32 s22, s84
	s_add_u32 s84, s24, 0x16e00000
	s_addc_u32 s85, s25, 0
	s_add_u32 s0, s24, 0x17800000
	s_addc_u32 s1, s25, 0
	v_writelane_b32 v254, s0, 40
	s_mul_i32 s92, s77, 0x640
	v_readlane_b32 s4, v253, 28
	v_writelane_b32 v254, s1, 41
	s_mov_b64 s[0:1], s[82:83]
	s_lshl_b64 s[0:1], s[92:93], 2
	v_readlane_b32 s6, v253, 30
	v_readlane_b32 s7, v253, 31
	s_add_u32 s0, s6, s0
	s_addc_u32 s1, s7, s1
	v_writelane_b32 v254, s0, 42
	s_lshl_b32 s92, s77, 14
	v_readlane_b32 s8, v253, 32
	v_writelane_b32 v254, s1, 43
	s_lshl_b64 s[0:1], s[92:93], 2
	v_readlane_b32 s9, v253, 33
	s_add_u32 s86, s8, s0
	s_addc_u32 s87, s9, s1
	s_lshl_b32 s92, s77, 9
	v_readlane_b32 s10, v253, 34
	s_lshl_b64 s[2:3], s[92:93], 2
	v_readlane_b32 s11, v253, 35
	s_add_u32 s6, s10, s2
	v_readlane_b32 s12, v253, 36
	s_addc_u32 s7, s11, s3
	v_readlane_b32 s13, v253, 37
	s_add_u32 s66, s12, s0
	v_readlane_b32 s14, v253, 38
	s_addc_u32 s67, s13, s1
	v_readlane_b32 s15, v253, 39
	v_writelane_b32 v254, s6, 44
	s_add_u32 s0, s14, s2
	s_addc_u32 s1, s15, s3
	v_writelane_b32 v254, s7, 45
	v_writelane_b32 v254, s0, 46
	s_mul_i32 s92, s77, 0x600
	v_readlane_b32 s16, v253, 40
	v_writelane_b32 v254, s1, 47
	s_lshl_b64 s[0:1], s[92:93], 2
	v_readlane_b32 s17, v253, 41
	s_add_u32 s0, s16, s0
	s_addc_u32 s1, s17, s1
	v_readlane_b32 s18, v253, 42
	v_writelane_b32 v254, s0, 48
	v_readlane_b32 s19, v253, 43
	v_readlane_b32 s5, v253, 29
	v_writelane_b32 v254, s1, 49
	s_add_u32 s0, s18, s2
	s_addc_u32 s1, s19, s3
	v_writelane_b32 v254, s0, 50
	s_mov_b32 s23, s93
	s_nop 0
	v_writelane_b32 v254, s1, 51
	s_add_u32 s0, s80, s2
	s_addc_u32 s1, s81, s3
	v_writelane_b32 v254, s0, 52
	s_lshl_b32 s92, s77, 11
	s_nop 0
	v_writelane_b32 v254, s1, 53
	s_lshl_b64 s[0:1], s[92:93], 2
	s_add_u32 s0, s4, s0
	s_addc_u32 s1, s5, s1
	s_add_u32 s42, s24, 0x1ba00000
	s_addc_u32 s43, s25, 0
	s_add_u32 s39, s24, 0x1da00000
	v_writelane_b32 v254, s0, 54
	s_addc_u32 s41, s25, 0
	v_readlane_b32 s4, v253, 12
	v_writelane_b32 v254, s1, 55
	s_add_u32 s0, s24, 0x1db00000
	v_writelane_b32 v254, s0, 56
	s_addc_u32 s0, s25, 0
	v_writelane_b32 v254, s0, 57
	s_add_u32 s0, s24, 0x1df00000
	v_writelane_b32 v254, s0, 58
	s_addc_u32 s0, s25, 0
	s_lshl_b32 s92, s77, 8
	v_writelane_b32 v254, s0, 59
	s_lshl_b64 s[0:1], s[92:93], 2
	v_readlane_b32 s14, v253, 22
	v_readlane_b32 s15, v253, 23
	s_add_u32 s90, s14, s0
	s_addc_u32 s91, s15, s1
	s_lshl_b32 s92, s77, 3
	v_readlane_b32 s18, v253, 26
	s_lshl_b64 s[0:1], s[92:93], 2
	v_readlane_b32 s19, v253, 27
	s_add_u32 s0, s18, s0
	v_writelane_b32 v254, s77, 60
	s_addc_u32 s1, s19, s1
	v_writelane_b32 v254, s0, 61
	v_readlane_b32 s5, v253, 13
	v_readlane_b32 s6, v253, 14
	v_writelane_b32 v254, s1, 62
	s_mov_b32 s0, s22
	v_writelane_b32 v254, s0, 63
	v_readlane_b32 s7, v253, 15
	v_readlane_b32 s8, v253, 16
	v_writelane_b32 v252, s1, 0
	s_lshl_b64 s[0:1], s[22:23], 2
	s_add_u32 s0, s24, s0
	v_writelane_b32 v252, s24, 1
	s_addc_u32 s1, s25, s1
	v_readlane_b32 s9, v253, 17
	v_writelane_b32 v252, s25, 2
	v_writelane_b32 v252, s0, 3
	v_readlane_b32 s10, v253, 18
	v_readlane_b32 s11, v253, 19
	v_writelane_b32 v252, s1, 4
	v_writelane_b32 v252, s42, 5
	v_readlane_b32 s12, v253, 20
	v_readlane_b32 s13, v253, 21
	v_writelane_b32 v252, s43, 6
	v_writelane_b32 v252, s39, 7
	v_readlane_b32 s16, v253, 24
	v_readlane_b32 s17, v253, 25
	v_writelane_b32 v252, s41, 8
	v_mov_b32_e32 v255, -1
	s_branch .LBB0_211

; #define LAS __attribute__((address_space(3)))
; __device__ __forceinline__ int next_item(unsigned* ctr, LAS unsigned* slot) {
;     __syncthreads();
;     if (threadIdx.x == 0) *slot = atomicAdd(ctr, 1u);
;     __syncthreads();
;     return (int)*slot;
.LBB0_211:
	s_waitcnt lgkmcnt(0)
	s_barrier
	s_mov_b64 s[0:1], exec
	v_readlane_b32 s2, v253, 0
	v_readlane_b32 s3, v253, 1
	s_and_b64 s[2:3], s[0:1], s[2:3]
	s_mov_b64 exec, s[2:3]
	s_cbranch_execz .LBB0_213
	v_cmp_ne_u32_e32 vcc, -1, v255
	s_nop 1
	s_cbranch_vccnz .Lnx_a_have
	v_readlane_b32 s2, v252, 3
	v_readlane_b32 s3, v252, 4
	s_waitcnt vmcnt(0)
	s_nop 0
	v_mov_b64_e32 v[2:3], s[2:3]
	global_atomic_add v255, v[2:3], v213, off offset:8 sc0
	s_waitcnt vmcnt(0)
.Lnx_a_have:
	v_readlane_b32 s2, v254, 19
	s_nop 1
	v_mov_b32_e32 v2, s2
	s_waitcnt lgkmcnt(0)
	ds_write_b32 v2, v255
	v_mov_b32_e32 v255, -1



; #define LAS __attribute__((address_space(3)))
; template <int MODE>
; __device__ __forceinline__ void attn_item(const AttnP& p, int b, int h, int qb, LAS unsigned char* lds) {
;     ...
;     float inv0 = 1.f, inv1 = 0.f;
;     if (MODE != 1) { float l0 = lsum[0]; l0 += __shfl_xor(l0, 32); inv0 = 1.0f / l0; }
; __device__ __forceinline__ int next_item(unsigned* ctr, LAS unsigned* slot) {
;     __syncthreads();
;     if (threadIdx.x == 0) *slot = atomicAdd(ctr, 1u);
.LBB0_242:
	v_readlane_b32 s100, v252, 3
	v_readlane_b32 s101, v252, 4
	v_cmp_eq_u32_e32 vcc, 0, v210
	v_mov_b32_e32 v140, 1
	v_mov_b32_e32 v141, 0
	s_and_b64 vcc, vcc, exec
	s_cbranch_scc0 .Lnx_af
	s_mov_b64 exec, vcc
	global_atomic_add v255, v141, v140, s[100:101] offset:8 sc0
	s_mov_b64 exec, -1

; #define LAS __attribute__((address_space(3)))
; __device__ __forceinline__ int next_item(unsigned* ctr, LAS unsigned* slot) {
;     __syncthreads();
;     if (threadIdx.x == 0) *slot = atomicAdd(ctr, 1u);
; __global__ void __launch_bounds__(512) hymba_fwd(Args a) {
;     ...
;             float lam;
;             {
;                 const float* dl = a.diff_lambda + l * 256; int tl_ = threadIdx.x; asm volatile("" : "+v"(tl_)); const int lane = tl_ & 63;
;                 const float s1 = wave_sum(dl[lane] * dl[64 + lane]), s2 = wave_sum(dl[128 + lane] * dl[192 + lane]);
;                 const float lam_init = 0.8f - 0.6f * expf(-0.3f * (float)l);
;                 lam = expf(s1) - expf(s2) + lam_init;
;                 const float lam_u = __int_as_float(__builtin_amdgcn_readfirstlane(__float_as_int(lam))), oml_u = __int_as_float(__builtin_amdgcn_readfirstlane(__float_as_int(1.0f - lam_init)));
;                 AttnP ap{proj, mixed, misc, a.qk_gain + l * 256, a.out_gain + l * 2048, biasT, a.forget_bias + l * 8, lam_u, oml_u};
;                 for (;;) {
;                     const int idx = next_item(ctl + pb + 3 + 16 * rep, qslot);
.LBB0_465:
	s_andn2_b64 vcc, exec, s[0:1]
	s_cbranch_vccnz .LBB0_587
	v_cvt_f32_u32_e32 v0, s77
	s_mov_b32 s20, 0x3fb8aa3b
	s_lshl_b32 s92, s77, 8
	v_readlane_b32 s4, v253, 12
	v_mul_f32_e32 v0, 0xbe99999a, v0
	v_mul_f32_e32 v2, 0x3fb8aa3b, v0
	v_fma_f32 v3, v0, s20, -v2
	v_rndne_f32_e32 v4, v2
	v_fmac_f32_e32 v3, 0x32a5705f, v0
	v_sub_f32_e32 v2, v2, v4
	s_lshl_b64 s[0:1], s[92:93], 2
	v_readlane_b32 s16, v253, 24
	v_add_f32_e32 v2, v2, v3
	v_readlane_b32 s17, v253, 25
	s_add_u32 s2, s16, s0
	v_exp_f32_e32 v2, v2
	v_cvt_i32_f32_e32 v3, v4
	v_readlane_b32 s14, v253, 22
	s_addc_u32 s3, s17, s1
	v_readlane_b32 s15, v253, 23
	s_add_u32 s40, s14, s0
	v_readlane_b32 s5, v253, 13
	v_readlane_b32 s6, v253, 14
	v_readlane_b32 s7, v253, 15
	v_readlane_b32 s8, v253, 16
	v_readlane_b32 s9, v253, 17
	v_readlane_b32 s10, v253, 18
	v_readlane_b32 s11, v253, 19
	v_readlane_b32 s12, v253, 20
	v_readlane_b32 s13, v253, 21
	v_readlane_b32 s18, v253, 26
	v_readlane_b32 s19, v253, 27
	s_mov_b32 s22, 0xc2ce8ed0
	s_addc_u32 s41, s15, s1
	s_lshl_b32 s92, s77, 11
	v_ldexp_f32 v2, v2, v3
	v_cmp_ngt_f32_e32 vcc, s22, v0
	s_mov_b32 s23, 0x42b17218
	s_lshl_b64 s[0:1], s[92:93], 2
	v_readlane_b32 s4, v253, 28
	v_cndmask_b32_e32 v2, 0, v2, vcc
	v_cmp_nlt_f32_e32 vcc, s23, v0
	v_readlane_b32 s5, v253, 29
	s_add_u32 s54, s4, s0
	v_cndmask_b32_e32 v0, v220, v2, vcc
	s_addc_u32 s55, s5, s1
	s_mov_b64 s[0:1], s[68:69]
	s_mov_b64 s[4:5], s[82:83]
	v_mov_b32_e32 v2, v210
	v_and_b32_e32 v6, 64, v216
	v_and_b32_e32 v2, 63, v2
	v_lshlrev_b32_e32 v2, 2, v2
	global_load_dword v3, v2, s[2:3]
	global_load_dword v4, v2, s[2:3] offset:256
	v_add_u32_e32 v6, 64, v6
	v_xor_b32_e32 v7, 1, v216
	v_cmp_lt_i32_e32 vcc, v7, v6
	s_add_u32 s42, s0, 0x4000
	s_addc_u32 s43, s1, 0
	v_cndmask_b32_e32 v7, v216, v7, vcc
	v_lshlrev_b32_e32 v221, 2, v7
	s_add_u32 s44, s0, 0x17800000
	v_fmamk_f32 v0, v0, 0xbf19999a, v215
	s_addc_u32 s45, s1, 0
	s_add_u32 s46, s0, 0x6a00000
	s_mov_b32 s85, s93
	s_addc_u32 s47, s1, 0
	s_movk_i32 s75, 0x5ff
	s_mov_b32 s74, 0xf800000
	v_readlane_b32 s6, v253, 30
	v_readlane_b32 s7, v253, 31
	v_readlane_b32 s8, v253, 32
	v_readlane_b32 s9, v253, 33
	v_readlane_b32 s10, v253, 34
	v_readlane_b32 s11, v253, 35
	v_readlane_b32 s12, v253, 36
	v_readlane_b32 s13, v253, 37
	v_readlane_b32 s14, v253, 38
	v_readlane_b32 s15, v253, 39
	v_readlane_b32 s16, v253, 40
	v_readlane_b32 s17, v253, 41
	v_readlane_b32 s18, v253, 42
	v_readlane_b32 s19, v253, 43
	s_waitcnt vmcnt(0)
	v_mul_f32_e32 v5, v3, v4
	ds_bpermute_b32 v5, v221, v5
	s_waitcnt lgkmcnt(0)
	v_fmac_f32_e32 v5, v3, v4
	v_xor_b32_e32 v3, 2, v216
	v_cmp_lt_i32_e32 vcc, v3, v6
	v_xor_b32_e32 v4, 4, v216
	s_nop 0
	v_cndmask_b32_e32 v3, v216, v3, vcc
	v_lshlrev_b32_e32 v222, 2, v3
	ds_bpermute_b32 v3, v222, v5
	v_cmp_lt_i32_e32 vcc, v4, v6
	s_waitcnt lgkmcnt(0)
	v_add_f32_e32 v3, v5, v3
	v_cndmask_b32_e32 v4, v216, v4, vcc
	v_lshlrev_b32_e32 v223, 2, v4
	ds_bpermute_b32 v4, v223, v3
	s_waitcnt lgkmcnt(0)
	v_add_f32_e32 v3, v3, v4
	v_xor_b32_e32 v4, 8, v216
	v_cmp_lt_i32_e32 vcc, v4, v6
	s_nop 1
	v_cndmask_b32_e32 v4, v216, v4, vcc
	v_lshlrev_b32_e32 v224, 2, v4
	ds_bpermute_b32 v4, v224, v3
	s_waitcnt lgkmcnt(0)
	v_add_f32_e32 v3, v3, v4
	v_xor_b32_e32 v4, 16, v216
	v_cmp_lt_i32_e32 vcc, v4, v6
	s_nop 1
	v_cndmask_b32_e32 v4, v216, v4, vcc
	v_lshlrev_b32_e32 v225, 2, v4
	ds_bpermute_b32 v4, v225, v3
	s_waitcnt lgkmcnt(0)
	v_add_f32_e32 v3, v3, v4
	v_xor_b32_e32 v4, 32, v216
	v_cmp_lt_i32_e32 vcc, v4, v6
	s_nop 1
	v_cndmask_b32_e32 v4, v216, v4, vcc
	v_lshlrev_b32_e32 v226, 2, v4
	ds_bpermute_b32 v4, v226, v3
	s_waitcnt lgkmcnt(0)
	v_add_f32_e32 v3, v3, v4
	global_load_dword v4, v2, s[2:3] offset:512
	s_nop 0
	global_load_dword v2, v2, s[2:3] offset:768
	v_cmp_ngt_f32_e32 vcc, s22, v3
	v_readfirstlane_b32 s2, v0
	s_waitcnt vmcnt(0)
	v_mul_f32_e32 v5, v4, v2
	ds_bpermute_b32 v5, v221, v5
	v_sub_f32_e64 v227, 1.0, s2
	s_lshl_b64 s[2:3], s[84:85], 2
	s_add_u32 s48, s0, s2
	s_addc_u32 s49, s1, s3
	s_waitcnt lgkmcnt(0)
	v_fmac_f32_e32 v5, v4, v2
	ds_bpermute_b32 v2, v222, v5
	s_waitcnt lgkmcnt(0)
	v_add_f32_e32 v2, v5, v2
	ds_bpermute_b32 v4, v223, v2
	s_waitcnt lgkmcnt(0)
	v_add_f32_e32 v2, v2, v4
	ds_bpermute_b32 v4, v224, v2
	s_waitcnt lgkmcnt(0)
	v_add_f32_e32 v2, v2, v4
	ds_bpermute_b32 v4, v225, v2
	s_waitcnt lgkmcnt(0)
	v_add_f32_e32 v2, v2, v4
	ds_bpermute_b32 v4, v226, v2
	s_waitcnt lgkmcnt(0)
	v_add_f32_e32 v2, v2, v4
	v_mul_f32_e32 v4, 0x3fb8aa3b, v3
	v_fma_f32 v5, v3, s20, -v4
	v_rndne_f32_e32 v6, v4
	v_fmac_f32_e32 v5, 0x32a5705f, v3
	v_sub_f32_e32 v4, v4, v6
	v_add_f32_e32 v4, v4, v5
	v_exp_f32_e32 v4, v4
	v_cvt_i32_f32_e32 v5, v6
	v_ldexp_f32 v4, v4, v5
	v_cndmask_b32_e32 v4, 0, v4, vcc
	v_cmp_nlt_f32_e32 vcc, s23, v3
	s_nop 1
	v_cndmask_b32_e32 v3, v220, v4, vcc
	v_mul_f32_e32 v4, 0x3fb8aa3b, v2
	v_fma_f32 v5, v2, s20, -v4
	v_rndne_f32_e32 v6, v4
	v_fmac_f32_e32 v5, 0x32a5705f, v2
	v_sub_f32_e32 v4, v4, v6
	v_add_f32_e32 v4, v4, v5
	v_exp_f32_e32 v4, v4
	v_cvt_i32_f32_e32 v5, v6
	v_cmp_ngt_f32_e32 vcc, s22, v2
	v_ldexp_f32 v4, v4, v5
	s_nop 0
	v_cndmask_b32_e32 v4, 0, v4, vcc
	v_cmp_nlt_f32_e32 vcc, s23, v2
	s_nop 1
	v_cndmask_b32_e32 v2, v220, v4, vcc
	v_sub_f32_e32 v2, v3, v2
	v_add_f32_e32 v2, v0, v2
	s_nop 0
	v_readfirstlane_b32 s56, v2
	v_cmp_eq_u32_e64 s[100:101], 0, v210
	v_mov_b32_e32 v2, 1
	v_mov_b32_e32 v3, 0
	s_and_b64 s[100:101], s[100:101], exec
	s_cbranch_scc0 .Lnx_b0
	s_mov_b64 exec, s[100:101]
	global_atomic_add v255, v3, v2, s[48:49] offset:16 sc0
	s_mov_b64 exec, -1
.Lnx_b0:
	s_waitcnt vmcnt(0)
	s_branch .LBB0_470
.LBB0_467:
	v_cmp_eq_u32_e64 s[100:101], 0, v210
	v_mov_b32_e32 v130, 1
	v_mov_b32_e32 v131, 0
	s_and_b64 s[100:101], s[100:101], exec
	s_cbranch_scc0 .Lnx_bd
	s_mov_b64 exec, s[100:101]
	global_atomic_add v255, v131, v130, s[48:49] offset:16 sc0
	s_mov_b64 exec, -1

; #define LAS __attribute__((address_space(3)))
; __device__ __forceinline__ int next_item(unsigned* ctr, LAS unsigned* slot) {
;     __syncthreads();
;     if (threadIdx.x == 0) *slot = atomicAdd(ctr, 1u);
;     __syncthreads();
;     return (int)*slot;
.LBB0_470:
	s_barrier
	s_mov_b64 s[0:1], exec
	v_readlane_b32 s2, v253, 0
	v_readlane_b32 s3, v253, 1
	s_and_b64 s[2:3], s[0:1], s[2:3]
	s_mov_b64 exec, s[2:3]
	s_cbranch_execz .LBB0_472
	v_readlane_b32 s2, v254, 19
	s_nop 1
	v_mov_b32_e32 v2, s2
	s_waitcnt lgkmcnt(0)
	ds_write_b32 v2, v255

; #define LAS __attribute__((address_space(3)))
; template <int MODE>
; __device__ __forceinline__ void attn_item(const AttnP& p, int b, int h, int qb, LAS unsigned char* lds) {
;     ...
;     float inv0 = 1.f, inv1 = 0.f;
;     if (MODE != 1) { float l0 = lsum[0]; l0 += __shfl_xor(l0, 32); inv0 = 1.0f / l0; }
;     if (MODE == 0) { float l1 = lsum[NC - 1]; l1 += __shfl_xor(l1, 32); inv1 = p.lam / l1; }
;     float ss = 0.f;
; __device__ __forceinline__ int next_item(unsigned* ctr, LAS unsigned* slot) {
;     __syncthreads();
;     if (threadIdx.x == 0) *slot = atomicAdd(ctr, 1u);
.LBB0_490:
	v_cmp_eq_u32_e64 s[100:101], 0, v210
	v_mov_b32_e32 v38, 1
	v_mov_b32_e32 v39, 0
	s_and_b64 s[100:101], s[100:101], exec
	s_cbranch_scc0 .Lnx_bs
	s_mov_b64 exec, s[100:101]
	global_atomic_add v255, v39, v38, s[48:49] offset:16 sc0
	s_mov_b64 exec, -1

; __global__ void __launch_bounds__(512) hymba_fwd(Args a) {
	.amdhsa_kernel _Z9hymba_fwd4Args
		.amdhsa_group_segment_fixed_size 0
		.amdhsa_private_segment_fixed_size 0
		.amdhsa_kernarg_size 416
		.amdhsa_user_sgpr_count 2
		.amdhsa_user_sgpr_dispatch_ptr 0
		.amdhsa_user_sgpr_queue_ptr 0
		.amdhsa_user_sgpr_kernarg_segment_ptr 1
		.amdhsa_user_sgpr_dispatch_id 0
		.amdhsa_user_sgpr_kernarg_preload_length 0
		.amdhsa_user_sgpr_kernarg_preload_offset 0
		.amdhsa_user_sgpr_private_segment_size 0
		.amdhsa_uses_dynamic_stack 0
		.amdhsa_enable_private_segment 0
		.amdhsa_system_sgpr_workgroup_id_x 1
		.amdhsa_system_sgpr_workgroup_id_y 0
		.amdhsa_system_sgpr_workgroup_id_z 0
		.amdhsa_system_sgpr_workgroup_info 0
		.amdhsa_system_vgpr_workitem_id 2
		.amdhsa_next_free_vgpr 256
		.amdhsa_next_free_sgpr 102
		.amdhsa_accum_offset 256
		.amdhsa_reserve_vcc 1
		.amdhsa_float_round_mode_32 0
		.amdhsa_float_round_mode_16_64 0
		.amdhsa_float_denorm_mode_32 3
		.amdhsa_float_denorm_mode_16_64 3
		.amdhsa_dx10_clamp 1
		.amdhsa_ieee_mode 1
		.amdhsa_fp16_overflow 0
		.amdhsa_tg_split 0
		.amdhsa_exception_fp_ieee_invalid_op 0
		.amdhsa_exception_fp_denorm_src 0
		.amdhsa_exception_fp_ieee_div_zero 0
		.amdhsa_exception_fp_ieee_overflow 0
		.amdhsa_exception_fp_ieee_underflow 0
		.amdhsa_exception_fp_ieee_inexact 0
		.amdhsa_exception_int_div_zero 0
	.end_amdhsa_kernel

; __global__ void __launch_bounds__(512) hymba_fwd(Args a) {
amdhsa.kernels:
  - .agpr_count:     0
    .args:
      - .offset:         0
        .size:           160
        .value_kind:     by_value
      - .offset:         160
        .size:           4
        .value_kind:     hidden_block_count_x
      - .offset:         164
        .size:           4
        .value_kind:     hidden_block_count_y
      - .offset:         168
        .size:           4
        .value_kind:     hidden_block_count_z
      - .offset:         172
        .size:           2
        .value_kind:     hidden_group_size_x
      - .offset:         174
        .size:           2
        .value_kind:     hidden_group_size_y
      - .offset:         176
        .size:           2
        .value_kind:     hidden_group_size_z
      - .offset:         178
        .size:           2
        .value_kind:     hidden_remainder_x
      - .offset:         180
        .size:           2
        .value_kind:     hidden_remainder_y
      - .offset:         182
        .size:           2
        .value_kind:     hidden_remainder_z
      - .offset:         200
        .size:           8
        .value_kind:     hidden_global_offset_x
      - .offset:         208
        .size:           8
        .value_kind:     hidden_global_offset_y
      - .offset:         216
        .size:           8
        .value_kind:     hidden_global_offset_z
      - .offset:         224
        .size:           2
        .value_kind:     hidden_grid_dims
      - .offset:         248
        .size:           8
        .value_kind:     hidden_multigrid_sync_arg
      - .offset:         280
        .size:           4
        .value_kind:     hidden_dynamic_lds_size
    .group_segment_fixed_size: 0
    .kernarg_segment_align: 8
    .kernarg_segment_size: 416
    .language:       OpenCL C
    .language_version:
      - 2
      - 0
    .max_flat_workgroup_size: 512
    .name:           _Z9hymba_fwd4Args
    .private_segment_fixed_size: 0
    .sgpr_count:     108
    .sgpr_spill_count: 144
    .symbol:         _Z9hymba_fwd4Args.kd
    .uniform_work_group_size: 1
    .uses_dynamic_stack: false
    .vgpr_count:     256
    .vgpr_spill_count: 0
    .wavefront_size: 64
